# E35: E27 + hazard nop before each srcC=0 MFMA removed (wait-state minimisation alone), pad keeps later code in place
# speedup vs baseline: 1.0013x; 1.0013x over previous
; template <class MB> __device__ __forceinline__ void la_soft(LA& st, f32x16& s, const TP& t, bf16x8& pf0, bf16x8& pf1) {
;     float mx = NEGBIG;
; #pragma unroll
;     for (int r = 0; r < 16; ++r) { s[r] = MB::apply(t, r, s[r]); mx = __builtin_fmaxf(mx, s[r]); }
;     { auto rr = __builtin_amdgcn_permlane32_swap(__float_as_uint(mx), __float_as_uint(mx), false, false); mx = __builtin_fmaxf(__uint_as_float(rr[0]), __uint_as_float(rr[1])); }
;     if (__any(mx > st.m)) { const float mn = __builtin_fmaxf(st.m, mx), alpha = __builtin_amdgcn_exp2f(st.m - mn); st.m = mn; st.l *= alpha; st.o0 *= alpha; st.o1 *= alpha; }
; template <class MB, int V1, class VS> __device__ __forceinline__ void la_step2(LA& sa, LA& sb, const bf16x8 (&qa)[4], const bf16x8 (&qb)[4], Frag& f, const char* kb, const VS& vs, const TP& t, const TP& n) {
;     bf16x8 pa0, pa1;
;     { f32x16 s0 = zero16();
; #pragma unroll
;       for (int d0 = 0; d0 < 4; ++d0) s0 = __builtin_amdgcn_mfma_f32_32x32x16_bf16(f.k[d0], qa[d0], s0, 0, 0, 0);
;       la_soft<MB>(sa, s0, t, pa0, pa1); }
.LBB0_661:
	s_add_i32 s4, s7, s9
	s_addk_i32 s4, 0xffa0
	s_cmpk_lt_u32 s4, 0x4000
	v_lshl_add_u32 v64, v64, 1, v148
	s_cselect_b64 s[4:5], -1, 0
	s_cmpk_lg_i32 s9, 0xc0
	v_add_u32_e32 v65, 0x9000, v64
	s_cselect_b64 s[10:11], -1, 0
	ds_read_b128 v[136:139], v65 offset:41472
	ds_read_b128 v[128:131], v65 offset:41504
	ds_read_b128 v[140:143], v64 offset:36864
	ds_read_b128 v[132:135], v64 offset:36896
	s_and_b64 vcc, s[10:11], s[4:5]
	v_add_u32_e32 v150, 0x80, v152
	v_mov_b32_e32 v64, s53
	v_cndmask_b32_e32 v167, v64, v150, vcc
	ds_read2_b32 v[154:155], v167 offset1:1
	s_waitcnt vmcnt(3)
	v_mfma_f32_32x32x16_bf16 v[64:79], v[124:127], v[96:99], 0
	s_waitcnt vmcnt(2)
	v_mfma_f32_32x32x16_bf16 v[64:79], v[120:123], v[88:91], v[64:79]
	s_waitcnt vmcnt(1)
	v_mfma_f32_32x32x16_bf16 v[64:79], v[116:119], v[92:95], v[64:79]
	s_waitcnt vmcnt(0)
	v_mfma_f32_32x32x16_bf16 v[64:79], v[112:115], v[100:103], v[64:79]
	s_waitcnt lgkmcnt(0)
	s_nop 10
	v_add_f32_e32 v154, v64, v154
	v_add_f32_e32 v153, v65, v155
	ds_read2_b32 v[64:65], v167 offset0:2 offset1:3
	v_max3_f32 v157, v154, s2, v153
	s_waitcnt lgkmcnt(0)
	v_add_f32_e32 v156, v66, v64
	v_add_f32_e32 v155, v67, v65
	ds_read2_b32 v[64:65], v167 offset0:4 offset1:5
	v_max3_f32 v66, v157, v156, v155
	s_waitcnt lgkmcnt(0)
	v_add_f32_e32 v158, v68, v64
	v_add_f32_e32 v157, v69, v65
	ds_read2_b32 v[64:65], v167 offset0:6 offset1:7
	v_max3_f32 v66, v66, v158, v157
	s_waitcnt lgkmcnt(0)
	v_add_f32_e32 v160, v70, v64
	v_add_f32_e32 v159, v71, v65
	ds_read2_b32 v[64:65], v167 offset0:16 offset1:17
	v_max3_f32 v66, v66, v160, v159
	s_waitcnt lgkmcnt(0)
	v_add_f32_e32 v162, v72, v64
	v_add_f32_e32 v161, v73, v65
	ds_read2_b32 v[64:65], v167 offset0:18 offset1:19
	v_max3_f32 v66, v66, v162, v161
	s_waitcnt lgkmcnt(0)
	v_add_f32_e32 v166, v74, v64
	v_add_f32_e32 v165, v75, v65
	ds_read2_b32 v[64:65], v167 offset0:20 offset1:21
	v_max3_f32 v66, v66, v166, v165
	s_waitcnt lgkmcnt(0)
	v_add_f32_e32 v164, v76, v64
	v_add_f32_e32 v163, v77, v65
	ds_read2_b32 v[64:65], v167 offset0:22 offset1:23
	v_max3_f32 v66, v66, v164, v163
	s_waitcnt lgkmcnt(0)
	v_add_f32_e32 v168, v78, v64
	v_add_f32_e32 v167, v79, v65
	v_max3_f32 v64, v66, v168, v167
	v_mov_b32_e32 v65, v64
	s_nop 1
	v_permlane32_swap_b32_e32 v64, v65
	v_max_f32_e32 v65, v65, v65
	v_max_f32_e32 v64, v64, v64
	v_max_f32_e32 v64, v64, v65
	v_cmp_gt_f32_e32 vcc, v64, v151
	s_cbranch_vccz .LBB0_663
	v_max_f32_e32 v64, v64, v64
	v_max_f32_e32 v65, v151, v151
	v_max_f32_e32 v65, v65, v64
	v_sub_f32_e32 v64, v151, v65
	v_exp_f32_e32 v64, v64
	v_mov_b32_e32 v151, v65
	v_mul_f32_e32 v147, v64, v147
	v_pk_mul_f32 v[46:47], v[64:65], v[46:47] op_sel_hi:[0,1]
	v_pk_mul_f32 v[44:45], v[64:65], v[44:45] op_sel_hi:[0,1]
	v_pk_mul_f32 v[42:43], v[64:65], v[42:43] op_sel_hi:[0,1]
	v_pk_mul_f32 v[40:41], v[64:65], v[40:41] op_sel_hi:[0,1]
	v_pk_mul_f32 v[38:39], v[64:65], v[38:39] op_sel_hi:[0,1]
	v_pk_mul_f32 v[36:37], v[64:65], v[36:37] op_sel_hi:[0,1]
	v_pk_mul_f32 v[34:35], v[64:65], v[34:35] op_sel_hi:[0,1]
	v_pk_mul_f32 v[32:33], v[64:65], v[32:33] op_sel_hi:[0,1]
	v_pk_mul_f32 v[62:63], v[64:65], v[62:63] op_sel_hi:[0,1]
	v_pk_mul_f32 v[60:61], v[64:65], v[60:61] op_sel_hi:[0,1]
	v_pk_mul_f32 v[58:59], v[64:65], v[58:59] op_sel_hi:[0,1]
	v_pk_mul_f32 v[56:57], v[64:65], v[56:57] op_sel_hi:[0,1]
	v_pk_mul_f32 v[54:55], v[64:65], v[54:55] op_sel_hi:[0,1]
	v_pk_mul_f32 v[52:53], v[64:65], v[52:53] op_sel_hi:[0,1]
	v_pk_mul_f32 v[50:51], v[64:65], v[50:51] op_sel_hi:[0,1]
	v_pk_mul_f32 v[48:49], v[64:65], v[48:49] op_sel_hi:[0,1]

; template <class MB> __device__ __forceinline__ void la_soft(LA& st, f32x16& s, const TP& t, bf16x8& pf0, bf16x8& pf1) {
;     float mx = NEGBIG;
; #pragma unroll
;     for (int r = 0; r < 16; ++r) { s[r] = MB::apply(t, r, s[r]); mx = __builtin_fmaxf(mx, s[r]); }
;     { auto rr = __builtin_amdgcn_permlane32_swap(__float_as_uint(mx), __float_as_uint(mx), false, false); mx = __builtin_fmaxf(__uint_as_float(rr[0]), __uint_as_float(rr[1])); }
;     if (__any(mx > st.m)) { const float mn = __builtin_fmaxf(st.m, mx), alpha = __builtin_amdgcn_exp2f(st.m - mn); st.m = mn; st.l *= alpha; st.o0 *= alpha; st.o1 *= alpha; }
; template <class MB, int V1, class VS> __device__ __forceinline__ void la_step2(LA& sa, LA& sb, const bf16x8 (&qa)[4], const bf16x8 (&qb)[4], Frag& f, const char* kb, const VS& vs, const TP& t, const TP& n) {
;     bf16x8 pa0, pa1;
;     { f32x16 s0 = zero16();
; #pragma unroll
;       for (int d0 = 0; d0 < 4; ++d0) s0 = __builtin_amdgcn_mfma_f32_32x32x16_bf16(f.k[d0], qa[d0], s0, 0, 0, 0);
;       la_soft<MB>(sa, s0, t, pa0, pa1); }
.LBB0_673:
	v_lshlrev_b32_e32 v64, 1, v73
	v_ashrrev_i32_e32 v65, 31, v64
	v_lshl_add_u64 v[64:65], s[6:7], 0, v[64:65]
	v_add_co_u32_e32 v66, vcc, s80, v64
	s_add_i32 s8, s11, s13
	s_nop 0
	v_addc_co_u32_e32 v67, vcc, 0, v65, vcc
	global_load_dwordx4 v[128:131], v[66:67], off offset:2080
	global_load_dwordx4 v[136:139], v[66:67], off offset:2048
	global_load_dwordx4 v[132:135], v[64:65], off offset:32
	global_load_dwordx4 v[140:143], v[64:65], off
	s_cmpk_lt_u32 s8, 0x4000
	s_cselect_b64 s[8:9], -1, 0
	s_cmpk_lg_i32 s12, 0x480
	s_cselect_b64 s[14:15], -1, 0
	v_add_u32_e32 v197, s12, v195
	s_and_b64 vcc, s[14:15], s[8:9]
	v_add_u32_e32 v64, 0x80, v197
	v_mov_b32_e32 v65, s53
	v_cndmask_b32_e32 v212, v65, v64, vcc
	ds_read2_b32 v[200:201], v212 offset1:1
	s_waitcnt vmcnt(7)
	v_mfma_f32_32x32x16_bf16 v[64:79], v[124:127], v[80:83], 0
	s_waitcnt vmcnt(6)
	v_mfma_f32_32x32x16_bf16 v[64:79], v[120:123], v[84:87], v[64:79]
	s_waitcnt vmcnt(5)
	v_mfma_f32_32x32x16_bf16 v[64:79], v[116:119], v[96:99], v[64:79]
	s_waitcnt vmcnt(4)
	v_mfma_f32_32x32x16_bf16 v[64:79], v[112:115], v[100:103], v[64:79]
	s_waitcnt lgkmcnt(0)
	s_nop 10
	v_add_f32_e32 v199, v64, v200
	v_add_f32_e32 v198, v65, v201
	ds_read2_b32 v[64:65], v212 offset0:2 offset1:3
	v_max3_f32 v202, v199, s2, v198
	s_waitcnt lgkmcnt(0)
	v_add_f32_e32 v201, v66, v64
	v_add_f32_e32 v200, v67, v65
	ds_read2_b32 v[64:65], v212 offset0:4 offset1:5
	v_max3_f32 v66, v202, v201, v200
	s_waitcnt lgkmcnt(0)
	v_add_f32_e32 v203, v68, v64
	v_add_f32_e32 v202, v69, v65
	ds_read2_b32 v[64:65], v212 offset0:6 offset1:7
	v_max3_f32 v66, v66, v203, v202
	s_waitcnt lgkmcnt(0)
	v_add_f32_e32 v205, v70, v64
	v_add_f32_e32 v204, v71, v65
	ds_read2_b32 v[64:65], v212 offset0:16 offset1:17
	v_max3_f32 v66, v66, v205, v204
	s_waitcnt lgkmcnt(0)
	v_add_f32_e32 v207, v72, v64
	v_add_f32_e32 v206, v73, v65
	ds_read2_b32 v[64:65], v212 offset0:18 offset1:19
	v_max3_f32 v66, v66, v207, v206
	s_waitcnt lgkmcnt(0)
	v_add_f32_e32 v211, v74, v64
	v_add_f32_e32 v210, v75, v65
	ds_read2_b32 v[64:65], v212 offset0:20 offset1:21
	v_max3_f32 v66, v66, v211, v210
	s_waitcnt lgkmcnt(0)
	v_add_f32_e32 v209, v76, v64
	v_add_f32_e32 v208, v77, v65
	ds_read2_b32 v[64:65], v212 offset0:22 offset1:23
	v_max3_f32 v66, v66, v209, v208
	s_waitcnt lgkmcnt(0)
	v_add_f32_e32 v213, v78, v64
	v_add_f32_e32 v212, v79, v65
	v_max3_f32 v64, v66, v213, v212
	v_mov_b32_e32 v65, v64
	s_nop 1
	v_permlane32_swap_b32_e32 v64, v65
	v_max_f32_e32 v65, v65, v65
	v_max_f32_e32 v64, v64, v64
	v_max_f32_e32 v64, v64, v65
	v_cmp_gt_f32_e32 vcc, v64, v196
	s_cbranch_vccz .LBB0_675
	v_max_f32_e32 v64, v64, v64
	v_max_f32_e32 v65, v196, v196
	v_max_f32_e32 v65, v65, v64
	v_sub_f32_e32 v64, v196, v65
	v_exp_f32_e32 v64, v64
	v_mov_b32_e32 v196, v65
	v_mul_f32_e32 v193, v193, v64
	v_pk_mul_f32 v[62:63], v[62:63], v[64:65] op_sel_hi:[1,0]
	v_pk_mul_f32 v[60:61], v[60:61], v[64:65] op_sel_hi:[1,0]
	v_pk_mul_f32 v[58:59], v[58:59], v[64:65] op_sel_hi:[1,0]
	v_pk_mul_f32 v[56:57], v[56:57], v[64:65] op_sel_hi:[1,0]
	v_pk_mul_f32 v[54:55], v[54:55], v[64:65] op_sel_hi:[1,0]
	v_pk_mul_f32 v[52:53], v[52:53], v[64:65] op_sel_hi:[1,0]
	v_pk_mul_f32 v[50:51], v[50:51], v[64:65] op_sel_hi:[1,0]
	v_pk_mul_f32 v[48:49], v[48:49], v[64:65] op_sel_hi:[1,0]
	v_pk_mul_f32 v[46:47], v[46:47], v[64:65] op_sel_hi:[1,0]
	v_pk_mul_f32 v[44:45], v[44:45], v[64:65] op_sel_hi:[1,0]
	v_pk_mul_f32 v[42:43], v[42:43], v[64:65] op_sel_hi:[1,0]
	v_pk_mul_f32 v[40:41], v[40:41], v[64:65] op_sel_hi:[1,0]
	v_pk_mul_f32 v[38:39], v[38:39], v[64:65] op_sel_hi:[1,0]
	v_pk_mul_f32 v[36:37], v[36:37], v[64:65] op_sel_hi:[1,0]
	v_pk_mul_f32 v[34:35], v[34:35], v[64:65] op_sel_hi:[1,0]
	v_pk_mul_f32 v[32:33], v[32:33], v[64:65] op_sel_hi:[1,0]

; template <class MB> __device__ __forceinline__ void la_soft(LA& st, f32x16& s, const TP& t, bf16x8& pf0, bf16x8& pf1) {
;     float mx = NEGBIG;
; #pragma unroll
;     for (int r = 0; r < 16; ++r) { s[r] = MB::apply(t, r, s[r]); mx = __builtin_fmaxf(mx, s[r]); }
;     { auto rr = __builtin_amdgcn_permlane32_swap(__float_as_uint(mx), __float_as_uint(mx), false, false); mx = __builtin_fmaxf(__uint_as_float(rr[0]), __uint_as_float(rr[1])); }
;     if (__any(mx > st.m)) { const float mn = __builtin_fmaxf(st.m, mx), alpha = __builtin_amdgcn_exp2f(st.m - mn); st.m = mn; st.l *= alpha; st.o0 *= alpha; st.o1 *= alpha; }
; template <class MB, int V1, class VS> __device__ __forceinline__ void la_step2(LA& sa, LA& sb, const bf16x8 (&qa)[4], const bf16x8 (&qb)[4], Frag& f, const char* kb, const VS& vs, const TP& t, const TP& n) {
;     bf16x8 pa0, pa1;
;     { f32x16 s0 = zero16();
; #pragma unroll
;       for (int d0 = 0; d0 < 4; ++d0) s0 = __builtin_amdgcn_mfma_f32_32x32x16_bf16(f.k[d0], qa[d0], s0, 0, 0, 0);
;       la_soft<MB>(sa, s0, t, pa0, pa1); }
.LBB0_678:
	v_lshl_add_u32 v64, s41, 2, v165
	v_ashrrev_i32_e32 v65, 31, v64
	v_lshl_add_u64 v[64:65], s[56:57], 0, v[64:65]
	v_add_co_u32_e32 v66, vcc, s80, v64
	s_cmp_eq_u32 s60, 8
	s_nop 0
	v_addc_co_u32_e32 v67, vcc, 0, v65, vcc
	global_load_dwordx4 v[128:131], v[66:67], off offset:2080
	global_load_dwordx4 v[136:139], v[66:67], off offset:2048
	global_load_dwordx4 v[132:135], v[64:65], off offset:32
	global_load_dwordx4 v[140:143], v[64:65], off
	s_cselect_b64 s[40:41], -1, 0
	v_add_u32_e32 v166, 0x200, v167
	v_mov_b32_e32 v64, s53
	v_cndmask_b32_e64 v183, v166, v64, s[40:41]
	ds_read2_b32 v[168:169], v183 offset1:1
	s_waitcnt vmcnt(7)
	v_mfma_f32_32x32x16_bf16 v[64:79], v[124:127], v[96:99], 0
	s_waitcnt vmcnt(6)
	v_mfma_f32_32x32x16_bf16 v[64:79], v[120:123], v[100:103], v[64:79]
	s_waitcnt vmcnt(5)
	v_mfma_f32_32x32x16_bf16 v[64:79], v[116:119], v[104:107], v[64:79]
	s_waitcnt vmcnt(4)
	v_mfma_f32_32x32x16_bf16 v[64:79], v[112:115], v[108:111], v[64:79]
	s_waitcnt lgkmcnt(0)
	s_nop 10
	v_add_f32_e32 v64, v64, v168
	v_cndmask_b32_e64 v168, v232, v64, s[6:7]
	v_add_f32_e32 v64, v65, v169
	v_cndmask_b32_e64 v169, v232, v64, s[8:9]
	ds_read2_b32 v[64:65], v183 offset0:2 offset1:3
	v_max3_f32 v172, v168, s2, v169
	s_waitcnt lgkmcnt(0)
	v_add_f32_e32 v64, v66, v64
	v_cndmask_b32_e64 v170, v232, v64, s[10:11]
	v_add_f32_e32 v64, v67, v65
	v_cndmask_b32_e64 v171, v232, v64, s[12:13]
	ds_read2_b32 v[64:65], v183 offset0:4 offset1:5
	v_max3_f32 v66, v172, v170, v171
	s_waitcnt lgkmcnt(0)
	v_add_f32_e32 v64, v68, v64
	v_cndmask_b32_e64 v172, v232, v64, s[14:15]
	v_add_f32_e32 v64, v69, v65
	v_cndmask_b32_e64 v173, v232, v64, s[16:17]
	ds_read2_b32 v[64:65], v183 offset0:6 offset1:7
	v_max3_f32 v66, v66, v172, v173
	s_waitcnt lgkmcnt(0)
	v_add_f32_e32 v64, v70, v64
	v_cndmask_b32_e64 v175, v232, v64, s[18:19]
	v_add_f32_e32 v64, v71, v65
	v_cndmask_b32_e64 v174, v232, v64, s[20:21]
	ds_read2_b32 v[64:65], v183 offset0:16 offset1:17
	v_max3_f32 v66, v66, v175, v174
	s_waitcnt lgkmcnt(0)
	v_add_f32_e32 v64, v72, v64
	v_cndmask_b32_e64 v176, v232, v64, s[22:23]
	v_add_f32_e32 v64, v73, v65
	v_cndmask_b32_e64 v177, v232, v64, s[24:25]
	ds_read2_b32 v[64:65], v183 offset0:18 offset1:19
	v_max3_f32 v66, v66, v176, v177
	s_waitcnt lgkmcnt(0)
	v_add_f32_e32 v64, v74, v64
	v_cndmask_b32_e64 v179, v232, v64, s[26:27]
	v_add_f32_e32 v64, v75, v65
	v_cndmask_b32_e64 v178, v232, v64, s[28:29]
	ds_read2_b32 v[64:65], v183 offset0:20 offset1:21
	v_max3_f32 v66, v66, v179, v178
	s_waitcnt lgkmcnt(0)
	v_add_f32_e32 v64, v76, v64
	v_cndmask_b32_e64 v180, v232, v64, s[30:31]
	v_add_f32_e32 v64, v77, v65
	v_cndmask_b32_e64 v182, v232, v64, s[34:35]
	ds_read2_b32 v[64:65], v183 offset0:22 offset1:23
	v_max3_f32 v66, v66, v180, v182
	s_waitcnt lgkmcnt(0)
	v_add_f32_e32 v64, v78, v64
	v_cndmask_b32_e64 v183, v232, v64, s[36:37]
	v_add_f32_e32 v64, v79, v65
	v_cndmask_b32_e64 v190, v232, v64, s[38:39]
	v_max3_f32 v64, v66, v183, v190
	v_mov_b32_e32 v65, v64
	s_nop 1
	v_permlane32_swap_b32_e32 v64, v65
	v_max_f32_e32 v65, v65, v65
	v_max_f32_e32 v64, v64, v64
	v_max_f32_e32 v64, v64, v65
	v_cmp_gt_f32_e32 vcc, v64, v162
	s_cbranch_vccz .LBB0_680
	v_max_f32_e32 v64, v64, v64
	v_max_f32_e32 v65, v162, v162
	v_max_f32_e32 v65, v65, v64
	v_sub_f32_e32 v64, v162, v65
	v_exp_f32_e32 v64, v64
	v_mov_b32_e32 v162, v65
	v_mul_f32_e32 v157, v157, v64
	v_pk_mul_f32 v[62:63], v[62:63], v[64:65] op_sel_hi:[1,0]
	v_pk_mul_f32 v[60:61], v[60:61], v[64:65] op_sel_hi:[1,0]
	v_pk_mul_f32 v[58:59], v[58:59], v[64:65] op_sel_hi:[1,0]
	v_pk_mul_f32 v[56:57], v[56:57], v[64:65] op_sel_hi:[1,0]
	v_pk_mul_f32 v[54:55], v[54:55], v[64:65] op_sel_hi:[1,0]
	v_pk_mul_f32 v[52:53], v[52:53], v[64:65] op_sel_hi:[1,0]
	v_pk_mul_f32 v[50:51], v[50:51], v[64:65] op_sel_hi:[1,0]
	v_pk_mul_f32 v[48:49], v[48:49], v[64:65] op_sel_hi:[1,0]
	v_pk_mul_f32 v[46:47], v[46:47], v[64:65] op_sel_hi:[1,0]
	v_pk_mul_f32 v[44:45], v[44:45], v[64:65] op_sel_hi:[1,0]
	v_pk_mul_f32 v[42:43], v[42:43], v[64:65] op_sel_hi:[1,0]
	v_pk_mul_f32 v[40:41], v[40:41], v[64:65] op_sel_hi:[1,0]
	v_pk_mul_f32 v[38:39], v[38:39], v[64:65] op_sel_hi:[1,0]
	v_pk_mul_f32 v[36:37], v[36:37], v[64:65] op_sel_hi:[1,0]
	v_pk_mul_f32 v[34:35], v[34:35], v[64:65] op_sel_hi:[1,0]
	v_pk_mul_f32 v[32:33], v[32:33], v[64:65] op_sel_hi:[1,0]

; __device__ __forceinline__ unsigned xb_lane() { unsigned l = __builtin_amdgcn_mbcnt_hi(~0u, __builtin_amdgcn_mbcnt_lo(~0u, 0u)); asm volatile("" : "+v"(l)); return l; }
; __device__ __forceinline__ void xcd_barrier(const XcdBarrier& b) {
;     asm volatile("s_waitcnt vmcnt(0)" ::: "memory");
;     __syncthreads();
;     if (b.lead != 0u && xb_lane() == 0u) {
;         unsigned* bar = b.bar;
;         __builtin_amdgcn_s_waitcnt(0);
;         unsigned nloc = b.st[0], nx = b.st[1];
;         if (nloc == 0u) { xcd_barrier_complete(bar, b.x, nloc, nx); b.st[0] = nloc; b.st[1] = nx; }
.LBB0_709:
	s_add_i32 s0, s36, 4
	s_cmp_lt_i32 s0, s51
	s_cselect_b64 s[4:5], -1, 0
	s_and_b64 s[6:7], s[46:47], s[4:5]
	s_andn2_b64 vcc, exec, s[6:7]
	s_cbranch_vccnz .LBB0_796
	v_readlane_b32 s8, v255, 3
	v_readlane_b32 s9, v255, 4
	s_mov_b64 s[6:7], -1
	s_and_b64 vcc, exec, s[8:9]
	s_cbranch_vccz .LBB0_783
	v_readfirstlane_b32 s6, v251
	v_readlane_b32 s1, v255, 2
	s_waitcnt vmcnt(0)
	s_cmp_eq_u32 s6, 0
	s_waitcnt vmcnt(0)
	s_barrier
	s_cbranch_scc1 .LBB0_782
	v_mov_b32_e32 v0, v252
	s_nop 0
	v_cmp_eq_u32_e32 vcc, 0, v0
	s_and_saveexec_b64 s[6:7], vcc
	s_cbranch_execz .LBB0_781
	v_readlane_b32 s8, v255, 26
	s_waitcnt vmcnt(0) expcnt(0) lgkmcnt(0)
	s_nop 0
	v_mov_b32_e32 v0, s8
	ds_read_b32 v2, v0
	v_readlane_b32 s8, v255, 27
	s_waitcnt lgkmcnt(0)
	v_cmp_ne_u32_e32 vcc, 0, v2
	v_mov_b32_e32 v0, s8
	ds_read_b32 v0, v0
	s_cbranch_vccnz .LBB0_745
	v_readlane_b32 s10, v255, 0
	v_readlane_b32 s11, v255, 1
	s_load_dwordx2 s[8:9], s[10:11], 0x4
	s_mov_b32 s15, 1
	s_waitcnt lgkmcnt(0)
	s_mul_i32 s14, s8, s3
	s_mul_i32 s14, s14, s9
	s_branch .LBB0_716
	s_nop 0
	s_nop 0
	s_nop 0
	s_nop 0
	s_nop 0
	s_nop 0
	s_nop 0
	s_nop 0
	s_nop 0
	s_nop 0
